# MLA work queue: the 36 largest (head, 256-query) items split into two 128-query half items (waves 0-3 compute) to cut the makespan
# speedup vs baseline: 1.0255x; 1.0255x over previous
.Lmla_skip_epi:
	s_mov_b64 s[16:17], 0
	s_branch .LBB0_1377
.LBB0_1376:
	s_cmp_lt_i32 s17, 0
	s_cbranch_scc1 .Lmla_skip_epi
	v_and_b32_e32 v41, 64, v208
	v_xor_b32_e32 v40, 16, v208
	v_add_u32_e32 v41, 64, v41
	v_cmp_lt_i32_e32 vcc, v40, v41
	v_xor_b32_e32 v42, 32, v208
	s_lshl_b32 s16, s16, 7
	v_cndmask_b32_e32 v40, v208, v40, vcc
	v_lshlrev_b32_e32 v43, 2, v40
	ds_bpermute_b32 v40, v43, v195
	v_cmp_lt_i32_e32 vcc, v42, v41
	s_ashr_i32 s17, s16, 31
	s_waitcnt lgkmcnt(0)
	v_add_f32_e32 v40, v195, v40
	v_cndmask_b32_e32 v41, v208, v42, vcc
	v_lshlrev_b32_e32 v50, 2, v41
	ds_bpermute_b32 v41, v50, v40
	s_waitcnt lgkmcnt(0)
	v_add_f32_e32 v42, v40, v41
	v_div_scale_f32 v44, s[18:19], v42, v42, 1.0
	v_rcp_f32_e32 v45, v44
	v_lshl_add_u64 v[40:41], s[16:17], 1, v[170:171]
	v_fma_f32 v46, -v44, v45, 1.0
	v_fmac_f32_e32 v45, v46, v45
	v_div_scale_f32 v46, vcc, 1.0, v42, 1.0
	v_mul_f32_e32 v47, v46, v45
	v_fma_f32 v48, -v44, v47, v46
	v_fmac_f32_e32 v47, v48, v45
	v_fma_f32 v44, -v44, v47, v46
	v_div_fmas_f32 v44, v44, v45, v47
	v_div_fixup_f32 v42, v44, v42, 1.0
	v_lshlrev_b64 v[44:45], 11, v[196:197]
	v_pk_mul_f32 v[46:47], v[94:95], v[42:43] op_sel_hi:[1,0]
	v_pk_mul_f32 v[48:49], v[92:93], v[42:43] op_sel_hi:[1,0]
	v_lshl_add_u64 v[44:45], v[40:41], 0, v[44:45]
	v_cvt_pk_bf16_f32 v48, v48, v49
	v_cvt_pk_bf16_f32 v49, v46, v47
	global_store_dwordx2 v[44:45], v[48:49], off
	v_pk_mul_f32 v[46:47], v[90:91], v[42:43] op_sel_hi:[1,0]
	v_pk_mul_f32 v[48:49], v[88:89], v[42:43] op_sel_hi:[1,0]
	s_nop 0
	v_cvt_pk_bf16_f32 v48, v48, v49
	v_cvt_pk_bf16_f32 v49, v46, v47
	global_store_dwordx2 v[44:45], v[48:49], off offset:32
	v_pk_mul_f32 v[46:47], v[86:87], v[42:43] op_sel_hi:[1,0]
	v_pk_mul_f32 v[48:49], v[84:85], v[42:43] op_sel_hi:[1,0]
	s_nop 0
	v_cvt_pk_bf16_f32 v48, v48, v49
	v_cvt_pk_bf16_f32 v49, v46, v47
	global_store_dwordx2 v[44:45], v[48:49], off offset:64
	v_pk_mul_f32 v[46:47], v[82:83], v[42:43] op_sel_hi:[1,0]
	v_pk_mul_f32 v[48:49], v[80:81], v[42:43] op_sel_hi:[1,0]
	s_nop 0
	v_cvt_pk_bf16_f32 v48, v48, v49
	v_cvt_pk_bf16_f32 v49, v46, v47
	global_store_dwordx2 v[44:45], v[48:49], off offset:96
	v_pk_mul_f32 v[46:47], v[78:79], v[42:43] op_sel_hi:[1,0]
	v_pk_mul_f32 v[48:49], v[76:77], v[42:43] op_sel_hi:[1,0]
	s_nop 0
	v_cvt_pk_bf16_f32 v48, v48, v49
	v_cvt_pk_bf16_f32 v49, v46, v47
	global_store_dwordx2 v[44:45], v[48:49], off offset:128
	v_pk_mul_f32 v[46:47], v[74:75], v[42:43] op_sel_hi:[1,0]
	v_pk_mul_f32 v[48:49], v[72:73], v[42:43] op_sel_hi:[1,0]
	ds_bpermute_b32 v43, v43, v193
	v_cvt_pk_bf16_f32 v48, v48, v49
	v_cvt_pk_bf16_f32 v49, v46, v47
	global_store_dwordx2 v[44:45], v[48:49], off offset:160
	s_waitcnt lgkmcnt(0)
	v_pk_mul_f32 v[38:39], v[38:39], v[42:43] op_sel_hi:[1,0]
	v_pk_mul_f32 v[36:37], v[36:37], v[42:43] op_sel_hi:[1,0]
	v_add_f32_e32 v43, v193, v43
	ds_bpermute_b32 v46, v50, v43
	v_cvt_pk_bf16_f32 v36, v36, v37
	v_cvt_pk_bf16_f32 v37, v38, v39
	global_store_dwordx2 v[44:45], v[36:37], off offset:192
	v_pk_mul_f32 v[34:35], v[34:35], v[42:43] op_sel_hi:[1,0]
	s_waitcnt lgkmcnt(0)
	v_add_f32_e32 v36, v43, v46
	v_div_scale_f32 v37, s[16:17], v36, v36, 1.0
	v_rcp_f32_e32 v38, v37
	v_pk_mul_f32 v[32:33], v[32:33], v[42:43] op_sel_hi:[1,0]
	s_mov_b64 s[16:17], 0
	v_cvt_pk_bf16_f32 v32, v32, v33
	v_cvt_pk_bf16_f32 v33, v34, v35
	global_store_dwordx2 v[44:45], v[32:33], off offset:224
	v_fma_f32 v32, -v37, v38, 1.0
	v_fmac_f32_e32 v38, v32, v38
	v_div_scale_f32 v32, vcc, 1.0, v36, 1.0
	v_mul_f32_e32 v33, v32, v38
	v_fma_f32 v34, -v37, v33, v32
	v_fmac_f32_e32 v33, v34, v38
	v_fma_f32 v32, -v37, v33, v32
	v_div_fmas_f32 v32, v32, v38, v33
	v_or_b32_e32 v34, 16, v196
	v_div_fixup_f32 v32, v32, v36, 1.0
	v_ashrrev_i32_e32 v35, 31, v34
	v_lshlrev_b64 v[34:35], 11, v[34:35]
	v_pk_mul_f32 v[30:31], v[30:31], v[32:33] op_sel_hi:[1,0]
	v_pk_mul_f32 v[28:29], v[28:29], v[32:33] op_sel_hi:[1,0]
	v_pk_mul_f32 v[26:27], v[26:27], v[32:33] op_sel_hi:[1,0]
	v_pk_mul_f32 v[24:25], v[24:25], v[32:33] op_sel_hi:[1,0]
	v_pk_mul_f32 v[22:23], v[22:23], v[32:33] op_sel_hi:[1,0]
	v_pk_mul_f32 v[20:21], v[20:21], v[32:33] op_sel_hi:[1,0]
	v_pk_mul_f32 v[18:19], v[18:19], v[32:33] op_sel_hi:[1,0]
	v_pk_mul_f32 v[16:17], v[16:17], v[32:33] op_sel_hi:[1,0]
	v_pk_mul_f32 v[14:15], v[14:15], v[32:33] op_sel_hi:[1,0]
	v_pk_mul_f32 v[12:13], v[12:13], v[32:33] op_sel_hi:[1,0]
	v_pk_mul_f32 v[10:11], v[10:11], v[32:33] op_sel_hi:[1,0]
	v_pk_mul_f32 v[8:9], v[8:9], v[32:33] op_sel_hi:[1,0]
	v_pk_mul_f32 v[6:7], v[6:7], v[32:33] op_sel_hi:[1,0]
	v_pk_mul_f32 v[4:5], v[4:5], v[32:33] op_sel_hi:[1,0]
	v_pk_mul_f32 v[2:3], v[2:3], v[32:33] op_sel_hi:[1,0]
	v_pk_mul_f32 v[0:1], v[0:1], v[32:33] op_sel_hi:[1,0]
	v_lshl_add_u64 v[34:35], v[40:41], 0, v[34:35]
	v_cvt_pk_bf16_f32 v28, v28, v29
	v_cvt_pk_bf16_f32 v29, v30, v31
	v_cvt_pk_bf16_f32 v24, v24, v25
	v_cvt_pk_bf16_f32 v25, v26, v27
	v_cvt_pk_bf16_f32 v20, v20, v21
	v_cvt_pk_bf16_f32 v21, v22, v23
	v_cvt_pk_bf16_f32 v16, v16, v17
	v_cvt_pk_bf16_f32 v17, v18, v19
	v_cvt_pk_bf16_f32 v12, v12, v13
	v_cvt_pk_bf16_f32 v13, v14, v15
	v_cvt_pk_bf16_f32 v8, v8, v9
	v_cvt_pk_bf16_f32 v9, v10, v11
	v_cvt_pk_bf16_f32 v4, v4, v5
	v_cvt_pk_bf16_f32 v5, v6, v7
	v_cvt_pk_bf16_f32 v0, v0, v1
	v_cvt_pk_bf16_f32 v1, v2, v3
	global_store_dwordx2 v[34:35], v[28:29], off
	global_store_dwordx2 v[34:35], v[24:25], off offset:32
	global_store_dwordx2 v[34:35], v[20:21], off offset:64
	global_store_dwordx2 v[34:35], v[16:17], off offset:96
	global_store_dwordx2 v[34:35], v[12:13], off offset:128
	global_store_dwordx2 v[34:35], v[8:9], off offset:160
	global_store_dwordx2 v[34:35], v[4:5], off offset:192
	global_store_dwordx2 v[34:35], v[0:1], off offset:224

.LBB0_1382:
	s_or_b64 exec, exec, s[16:17]
	s_add_i32 s16, 0, 0x14000
	v_mov_b32_e32 v0, s16
	s_waitcnt lgkmcnt(0)
	s_barrier
	ds_read_b32 v0, v0
	s_movk_i32 s16, 0x1a3
	s_waitcnt lgkmcnt(0)
	s_barrier
	v_cmp_lt_i32_e32 vcc, s16, v0
	v_readfirstlane_b32 s18, v0
	s_mov_b64 s[16:17], -1
	s_cbranch_vccnz .LBB0_1377
	s_cmp_lt_u32 s18, 0x48
	s_cbranch_scc1 .Lmla_half_item
	s_sub_i32 s18, s18, 0x48
	s_mul_hi_u32 s16, s18, 0x2aaaaaab
	s_sub_i32 s20, 57, s16
	s_mul_i32 s16, s16, 6
	s_sub_i32 s16, s18, s16
	s_mov_b32 s31, 4
	s_mov_b32 s30, s14
	v_lshl_add_u32 v196, s20, 8, v231
	s_branch .Lmla_item_ready
.Lmla_half_item:
	s_mul_hi_u32 s16, s18, 0x15555556
	s_sub_i32 s20, 63, s16
	s_mul_i32 s16, s16, 12
	s_sub_i32 s16, s18, s16
	s_and_b32 s3, s16, 1
	s_lshr_b32 s16, s16, 1
	s_lshl_b32 s31, s3, 1
	s_add_i32 s31, s31, 2
	s_and_b32 s30, s14, 1
	s_lshl_b32 s18, s3, 1
	s_add_i32 s30, s30, s18
	s_lshl_b32 s18, s20, 2
	s_not_b32 s18, s18
	s_cmp_lt_u32 s14, 2
	s_cselect_b32 s30, s30, s18
	v_and_b32_e32 v0, 0x7f, v231
	s_lshl_b32 s3, s3, 7
	v_lshl_add_u32 v196, s20, 8, v0
	v_add_u32_e32 v196, s3, v196
.Lmla_item_ready:
	s_ashr_i32 s17, s16, 31
	v_mad_i64_i32 v[0:1], s[18:19], v196, 6, s[16:17]
	v_mad_u64_u32 v[16:17], s[18:19], v0, s6, v[166:167]
	s_mov_b32 s18, 0x9000
	v_mad_i32_i24 v17, v1, s6, v17
	v_add_co_u32_e32 v18, vcc, s18, v16
	s_lshl_b32 s23, s20, 2
	s_nop 0
	v_addc_co_u32_e32 v19, vcc, 0, v17, vcc
	global_load_dwordx4 v[0:3], v[16:17], off offset:256
	global_load_dwordx4 v[4:7], v[16:17], off offset:320
	global_load_dwordx4 v[8:11], v[18:19], off offset:256
	global_load_dwordx4 v[12:15], v[18:19], off offset:320
	s_add_i32 s20, s23, s31
	s_mul_i32 s19, s16, 0x600000
	s_mul_hi_i32 s18, s16, 0x600000
	s_add_u32 s28, s10, s19
	s_addc_u32 s29, s11, s18
	s_lshl_b64 s[18:19], s[16:17], 22
	s_add_i32 s17, s15, 0
	v_lshl_add_u64 v[20:21], s[28:29], 0, v[172:173]
	v_mov_b32_e32 v193, v161
	v_mov_b32_e32 v195, v161
	s_add_i32 s21, s22, 0
	v_lshl_add_u64 v[22:23], s[28:29], 0, v[174:175]
	v_lshl_add_u64 v[24:25], s[28:29], 0, v[168:169]
	global_load_dwordx4 v[40:43], v[16:17], off
	global_load_dwordx4 v[44:47], v[16:17], off offset:64
	global_load_dwordx4 v[48:51], v[16:17], off offset:128
	global_load_dwordx4 v[52:55], v[16:17], off offset:192
	v_lshl_add_u64 v[16:17], v[20:21], 0, v[160:161]
	global_load_dwordx4 v[56:59], v[18:19], off
	global_load_dwordx4 v[60:63], v[18:19], off offset:64
	global_load_dwordx4 v[64:67], v[18:19], off offset:128
	global_load_dwordx4 v[68:71], v[18:19], off offset:192
	s_mov_b32 m0, s17
	v_lshl_add_u64 v[20:21], v[22:23], 0, v[192:193]
	v_lshl_add_u64 v[22:23], v[24:25], 0, v[194:195]
	s_mov_b64 s[28:29], 0x100
	v_lshl_add_u64 v[26:27], v[176:177], 0, s[18:19]
	v_lshl_add_u64 v[18:19], v[22:23], 0, s[28:29]
	v_lshl_add_u64 v[24:25], v[26:27], 0, v[178:179]
	v_lshl_add_u64 v[26:27], v[26:27], 0, v[180:181]
	v_mov_b32_e32 v32, v161
	v_mov_b32_e32 v33, v161
	v_mov_b32_e32 v34, v161
	v_mov_b32_e32 v35, v161
	v_mov_b64_e32 v[38:39], v[34:35]
	v_mov_b64_e32 v[74:75], v[34:35]
	v_mov_b64_e32 v[78:79], v[34:35]
	v_mov_b64_e32 v[82:83], v[34:35]
	v_mov_b64_e32 v[86:87], v[34:35]
	v_mov_b64_e32 v[90:91], v[34:35]
	v_mov_b64_e32 v[94:95], v[34:35]
	v_mov_b64_e32 v[28:29], v[32:33]
	v_ashrrev_i32_e32 v197, 31, v196
	v_lshl_add_u64 v[198:199], v[182:183], 0, s[18:19]
	v_lshl_add_u64 v[200:201], v[184:185], 0, s[18:19]
	v_mad_i64_i32 v[202:203], s[18:19], s16, v214, v[186:187]
	v_mad_i64_i32 v[204:205], s[18:19], s16, v214, v[188:189]
	v_mad_i64_i32 v[206:207], s[18:19], s16, v214, v[190:191]
	v_mov_b32_e32 v233, 0
	v_mov_b64_e32 v[36:37], v[32:33]
	v_mov_b64_e32 v[72:73], v[32:33]
	v_mov_b64_e32 v[76:77], v[32:33]
	v_mov_b64_e32 v[80:81], v[32:33]
	v_mov_b64_e32 v[84:85], v[32:33]
	v_mov_b64_e32 v[88:89], v[32:33]
	v_mov_b64_e32 v[92:93], v[32:33]
	v_mov_b32_e32 v234, 0
	v_mov_b32_e32 v193, 0
	v_mov_b32_e32 v195, 0
	v_mov_b64_e32 v[30:31], v[34:35]
	s_waitcnt vmcnt(11)
	ds_write_b128 v232, v[0:3]
	s_waitcnt vmcnt(10)
	ds_write_b128 v232, v[4:7] offset:1024
	s_waitcnt vmcnt(9)
	ds_write_b128 v232, v[8:11] offset:2048
	s_waitcnt vmcnt(8)
	ds_write_b128 v232, v[12:15] offset:3072
	global_load_lds_dwordx4 v[16:17], off
	s_mov_b32 m0, s21
	v_mov_b64_e32 v[12:13], v[32:33]
	global_load_lds_dwordx4 v[20:21], off
	s_add_i32 m0, s17, 0x4000
	v_mov_b64_e32 v[20:21], v[32:33]
	global_load_lds_dwordx4 v[18:19], off
	s_add_i32 m0, s17, 0x6000
	v_mov_b64_e32 v[16:17], v[32:33]
	global_load_lds_dwordx4 v[24:25], off
	s_add_i32 m0, s21, 0x6000
	v_mov_b64_e32 v[8:9], v[32:33]
	global_load_lds_dwordx4 v[26:27], off
	s_waitcnt vmcnt(0)
	v_mov_b64_e32 v[24:25], v[32:33]
	v_mov_b64_e32 v[4:5], v[32:33]
	v_mov_b64_e32 v[0:1], v[32:33]
	s_mov_b32 s21, 0
	s_add_i32 s17, s23, s30
	v_mov_b64_e32 v[26:27], v[34:35]
	v_mov_b64_e32 v[22:23], v[34:35]
	v_mov_b64_e32 v[18:19], v[34:35]
	v_mov_b64_e32 v[14:15], v[34:35]
	v_mov_b64_e32 v[10:11], v[34:35]
	v_mov_b64_e32 v[6:7], v[34:35]
	v_mov_b64_e32 v[2:3], v[34:35]
	s_waitcnt vmcnt(0) lgkmcnt(0)
	s_barrier
	s_add_i32 s18, s21, 1
	s_cmp_ge_u32 s18, s20
	s_cbranch_scc1 .LBB0_1385
